# P11 DPP butterflies + gather addressing; in-proj DMA/MFMA interleave + bias prefetch
# speedup vs baseline: 1.0230x; 1.0230x over previous
; DEVI int ltid() { int t = threadIdx.x; asm volatile("" : "+v"(t)); return t; }
; DEVI void phase11(const Params& P, int l, int pass, char* smem) {
;   const int ntok = pass ? 8192 : 8448, base = pass ? 8448 : 0;
;   const int tid = ltid(); const int w = tid >> 6, lane = tid & 63;
;   float* scl = (float*)smem;
;   float* sv = scl + 2048;
;   int* si = (int*)(sv + 256);
;   float* tops = (float*)(si + 256);
;   int* tope = (int*)(tops + 128);
;   float* wgt = (float*)(tope + 128);
;   float* svs = wgt + 128;
;   int* sis = (int*)(svs + 256);
;   float* red = (float*)(sis + 256);
;   float* stat = red + 4096;
;   const float* SC = (const float*)(P.ws + O_AU);
;   const unsigned char* UT = (const unsigned char*)(P.ws + O_UTB);
;   const unsigned char* VTb = (const unsigned char*)(P.ws + O_VTB);
;   const float* g2 = P.in[28] + l * 1024;
;   const float* b2 = P.in[29] + l * 1024;
;   bfu* xb = (bfu*)(P.ws + O_XB);
;   const unsigned long long ltmask = (1ull << lane) - 1ull;
;   for (int lt = blockIdx.x; lt < ntok; lt += gridDim.x) {
;     const int it = base + lt;
;     float* xr = xrow(P, it);
;     __syncthreads();
;     {
;       unsigned long long* s8 = reinterpret_cast<unsigned long long*>(const_cast<float*>(SC) + (long)lt * 2048);
;       unsigned long long* d8 = reinterpret_cast<unsigned long long*>(scl);
; #pragma unroll
;       for (int q = 0; q < 4; ++q)
;         d8[tid + 256 * q] = __hip_atomic_load(s8 + tid + 256 * q, __ATOMIC_RELAXED, __HIP_MEMORY_SCOPE_AGENT);
;     }
.LBB0_125:
	s_andn2_b64 vcc, exec, s[26:27]
	s_mov_b32 s0, s2
	s_cbranch_vccnz .LBB0_276
	s_add_i32 s1, s51, -1
	s_mov_b32 s0, s2
	s_cmp_eq_u32 s1, 0
	s_cselect_b64 s[40:41], -1, 0
	s_and_b64 s[42:43], s[40:41], exec
	s_movk_i32 s1, 0x2100
	s_cselect_b32 s1, s1, 0x2000
	v_readlane_b32 s58, v252, 32
	v_mov_b32_e32 v0, v93
	s_cmp_ge_i32 s58, s1
	s_cbranch_scc1 .LBB0_276
	v_and_b32_e32 v88, 63, v0
	v_lshlrev_b64 v[2:3], v0, -1
	v_not_b32_e32 v91, v3
	v_not_b32_e32 v100, v2
	v_lshlrev_b32_e32 v2, 4, v88
	v_mov_b32_e32 v3, v89
	v_lshl_add_u64 v[110:111], v[70:71], 0, v[2:3]
	v_lshl_add_u64 v[112:113], v[68:69], 0, v[2:3]
	v_and_b32_e32 v3, 32, v0
	v_and_b32_e32 v4, 64, v187
	v_cmp_eq_u32_e64 s[44:45], 0, v3
	v_xor_b32_e32 v3, 32, v187
	v_add_u32_e32 v4, 64, v4
	v_cmp_lt_i32_e32 vcc, v3, v4
	v_and_b32_e32 v7, 15, v0
	s_and_b64 s[40:41], s[40:41], exec
	v_cndmask_b32_e32 v3, v187, v3, vcc
	v_lshlrev_b32_e32 v125, 2, v3
	v_and_b32_e32 v3, 16, v0
	v_cmp_eq_u32_e64 s[46:47], 0, v3
	v_xor_b32_e32 v3, 16, v187
	v_cmp_lt_i32_e32 vcc, v3, v4
	s_cselect_b32 s82, 0, 0x2100
	s_lshl_b32 s40, s0, 10
	v_cndmask_b32_e32 v3, v187, v3, vcc
	v_lshlrev_b32_e32 v126, 2, v3
	v_and_b32_e32 v3, 8, v0
	v_cmp_eq_u32_e64 s[48:49], 0, v3
	v_xor_b32_e32 v3, 8, v187
	v_cmp_lt_i32_e32 vcc, v3, v4
	s_ashr_i32 s41, s40, 31
	v_readlane_b32 s4, v253, 14
	v_cndmask_b32_e32 v3, v187, v3, vcc
	v_lshlrev_b32_e32 v127, 2, v3
	v_xor_b32_e32 v3, 4, v187
	v_cmp_lt_i32_e32 vcc, v3, v4
	s_lshl_b64 s[40:41], s[40:41], 2
	v_readlane_b32 s18, v253, 28
	v_cndmask_b32_e32 v3, v187, v3, vcc
	v_lshlrev_b32_e32 v128, 2, v3
	v_xor_b32_e32 v3, 2, v187
	v_cmp_lt_i32_e32 vcc, v3, v4
	v_readlane_b32 s19, v253, 29
	s_add_u32 s54, s18, s40
	v_cndmask_b32_e32 v3, v187, v3, vcc
	v_lshlrev_b32_e32 v129, 2, v3
	v_xor_b32_e32 v3, 1, v187
	v_cmp_lt_i32_e32 vcc, v3, v4
	v_readlane_b32 s16, v253, 26
	s_addc_u32 s55, s19, s41
	v_cndmask_b32_e32 v3, v187, v3, vcc
	v_cmp_ne_u32_e32 vcc, 0, v7
	v_readlane_b32 s17, v253, 27
	s_add_u32 s56, s16, s40
	v_cndmask_b32_e64 v132, 0, 1, vcc
	v_cmp_lt_u32_e32 vcc, 1, v7
	v_ashrrev_i32_e32 v6, 6, v0
	s_addc_u32 s57, s17, s41
	v_cndmask_b32_e64 v133, 0, 1, vcc
	v_cmp_lt_u32_e32 vcc, 2, v7
	v_and_b32_e32 v109, 0xffffffc0, v0
	v_lshlrev_b32_e32 v104, 2, v0
	v_cndmask_b32_e64 v134, 0, 1, vcc
	v_cmp_lt_u32_e32 vcc, 3, v7
	v_lshlrev_b32_e32 v108, 7, v6
	s_movk_i32 s24, 0xf80
	v_cndmask_b32_e64 v135, 0, 1, vcc
	v_cmp_lt_u32_e32 vcc, 4, v7
	v_readlane_b32 s6, v253, 16
	v_readlane_b32 s7, v253, 17
	v_cndmask_b32_e64 v136, 0, 1, vcc
	v_cmp_lt_u32_e32 vcc, 5, v7
	v_ashrrev_i32_e32 v1, 31, v0
	v_lshlrev_b32_e32 v101, 3, v0
	v_cndmask_b32_e64 v137, 0, 1, vcc
	v_cmp_lt_u32_e32 vcc, 6, v7
	s_getpc_b64 s[42:43]
	s_add_u32 s42, s42, CAND_IJ@rel32@lo+4
	s_addc_u32 s43, s43, CAND_IJ@rel32@hi+12
	v_cndmask_b32_e64 v138, 0, 1, vcc
	v_cmp_lt_u32_e32 vcc, 7, v7
	s_movk_i32 s4, 0x80
	v_lshlrev_b32_e32 v130, 2, v3
	v_cndmask_b32_e64 v139, 0, 1, vcc
	v_cmp_lt_u32_e32 vcc, 8, v7
	v_and_b32_e32 v3, 7, v0
	v_mad_u64_u32 v[4:5], s[52:53], v6, s24, v[108:109]
	v_cndmask_b32_e64 v140, 0, 1, vcc
	v_cmp_lt_u32_e32 vcc, 9, v7
	v_ashrrev_i32_e32 v105, 31, v104
	s_movk_i32 s24, 0xf004
	v_cndmask_b32_e64 v141, 0, 1, vcc
	v_cmp_lt_u32_e32 vcc, 10, v7
	v_readlane_b32 s6, v252, 37
	v_lshlrev_b32_e32 v8, 2, v88
	v_cndmask_b32_e64 v142, 0, 1, vcc
	v_cmp_lt_u32_e32 vcc, 11, v7
	v_lshl_add_u64 v[102:103], v[0:1], 3, v[72:73]
	v_lshlrev_b32_e32 v1, 11, v6
	v_cndmask_b32_e64 v143, 0, 1, vcc
	v_cmp_lt_u32_e32 vcc, 12, v7
	v_and_b32_e32 v121, -16, v0
	v_sub_u32_e32 v122, v101, v104
	v_cndmask_b32_e64 v144, 0, 1, vcc
	v_cmp_lt_u32_e32 vcc, 13, v7
	v_lshl_add_u64 v[106:107], s[42:43], 0, v[88:89]
	v_lshlrev_b32_e32 v124, 5, v6
	v_cmp_gt_i32_e64 s[42:43], s4, v0
	v_cmp_eq_u32_e64 s[50:51], 0, v3
	v_mul_lo_u32 v3, v0, 12
	v_mul_lo_u32 v5, v6, s24
	v_cndmask_b32_e64 v145, 0, 1, vcc
	v_cmp_eq_u32_e32 vcc, 15, v7
	v_lshlrev_b64 v[6:7], 2, v[104:105]
	v_lshrrev_b32_e32 v0, 1, v0
	v_readlane_b32 s7, v252, 38
	v_readlane_b32 s23, v252, 31
	v_or_b32_e32 v120, 64, v88
	v_lshlrev_b32_e32 v123, 2, v121
	v_cmp_gt_u32_e64 s[40:41], 50, v88
	v_lshl_add_u32 v131, v88, 6, v4
	v_cmp_eq_u32_e64 s[52:53], 0, v88
	v_lshl_add_u64 v[114:115], v[104:105], 1, v[66:67]
	v_cndmask_b32_e64 v146, 0, 1, vcc
	v_lshl_add_u64 v[116:117], s[56:57], 0, v[6:7]
	v_lshl_add_u64 v[118:119], s[54:55], 0, v[6:7]
	v_add_u32_e32 v147, 0x2800, v108
	v_and_b32_e32 v148, 28, v0
	v_add_u32_e32 v149, v8, v1
	v_lshlrev_b32_e32 v150, 2, v2
	v_add_u32_e32 v151, v122, v3
	v_add_u32_e32 v152, v4, v5
	s_mov_b32 s74, s58
	v_readlane_b32 s5, v253, 15
	v_readlane_b32 s8, v253, 18
	v_readlane_b32 s9, v253, 19
	v_readlane_b32 s10, v253, 20
	v_readlane_b32 s11, v253, 21
	v_readlane_b32 s12, v253, 22
	v_readlane_b32 s13, v253, 23
	v_readlane_b32 s14, v253, 24
	v_readlane_b32 s15, v253, 25
	v_lshlrev_b32_e32 v232, 2, v104
	v_lshlrev_b32_e32 v250, 4, v88
	v_mov_b32_e32 v233, 0
	s_and_saveexec_b64 s[54:55], s[40:41]
	global_load_ubyte v233, v[106:107], off
	s_or_b64 exec, exec, s[54:55]
	s_mov_b32 s54, s74
	s_ashr_i32 s55, s74, 31
	s_lshl_b64 s[54:55], s[54:55], 13
	v_lshl_add_u64 v[218:219], v[102:103], 0, s[54:55]
	global_load_dwordx2 v[210:211], v[218:219], off sc1
	global_load_dwordx2 v[212:213], v[218:219], off offset:2048 sc1
	v_add_co_u32_e32 v218, vcc, 0x1000, v218
	s_nop 1
	v_addc_co_u32_e32 v219, vcc, 0, v219, vcc
	global_load_dwordx2 v[214:215], v[218:219], off sc1
	global_load_dwordx2 v[216:217], v[218:219], off offset:2048 sc1
	global_load_dwordx4 v[220:223], v[116:117], off
	global_load_dwordx4 v[224:227], v[118:119], off
	s_branch .LBB0_129

; DEVI void phase11(const Params& P, int l, int pass, char* smem) {
;     ...
;     f32x2 xv[8];
;     {
;       const float4* xp = reinterpret_cast<const float4*>(xr + lane * 16);
; #pragma unroll
;       for (int q = 0; q < 4; ++q) {
;         float4 a = xp[q];
;         xv[2 * q] = f32x2{a.x, a.y}; xv[2 * q + 1] = f32x2{a.z, a.w};
;       }
;     }
;     f32x2 oacc[8];
; #pragma unroll
;     for (int q = 0; q < 8; ++q) oacc[q] = f32x2{0.f, 0.f};
; #pragma unroll 1
;     for (int p0 = 0; p0 < 32; p0 += 8) {
;       uint4 ru[8], rv[8];
; #pragma unroll
;       for (int i = 0; i < 8; ++i) {
;         int e = tope[w * 32 + p0 + i];
;         ru[i] = *reinterpret_cast<const uint4*>(UT + (long)e * 1024 + lane * 16);
;         rv[i] = *reinterpret_cast<const uint4*>(VTb + (long)e * 1024 + lane * 16);
.LBB0_263:
	s_or_b64 exec, exec, s[54:55]
	s_lshl_b32 s24, s77, 12
	s_lshl_b32 s54, s77, 5
	s_or_b32 s24, s24, s83
	s_add_i32 s56, s54, s83
	s_and_b64 s[54:55], s[78:79], exec
	s_cselect_b32 s54, s24, s56
	s_ashr_i32 s55, s54, 31
	s_lshl_b64 s[54:55], s[54:55], 12
	s_and_b64 s[56:57], s[78:79], exec
	s_cselect_b32 s56, s28, s33
	s_cselect_b32 s24, s29, s93
	s_add_u32 s54, s56, s54
	s_addc_u32 s55, s24, s55
	s_waitcnt lgkmcnt(0)
	s_barrier
	v_readfirstlane_b32 s60, v110
	v_readfirstlane_b32 s61, v111
	v_readfirstlane_b32 s62, v112
	v_readfirstlane_b32 s63, v113
	global_load_dwordx4 v[0:3], v150, s[54:55] offset:48
	global_load_dwordx4 v[4:7], v150, s[54:55] offset:32
	global_load_dwordx4 v[8:11], v150, s[54:55] offset:16
	global_load_dwordx4 v[12:15], v150, s[54:55]
	global_load_dwordx4 v[228:231], v232, s[54:55]
	v_mov_b32_e32 v16, 0
	s_mov_b32 s24, -8
	v_mov_b32_e32 v153, v147
	v_mov_b32_e32 v17, v16
	v_mov_b32_e32 v18, v16
	v_mov_b32_e32 v19, v16
	v_mov_b32_e32 v28, v16
	v_mov_b32_e32 v29, v16
	v_mov_b32_e32 v30, v16
	v_mov_b32_e32 v31, v16
	v_mov_b32_e32 v24, v16
	v_mov_b32_e32 v25, v16
	v_mov_b32_e32 v26, v16
	v_mov_b32_e32 v27, v16
	v_mov_b32_e32 v20, v16
	v_mov_b32_e32 v21, v16
	v_mov_b32_e32 v22, v16
	v_mov_b32_e32 v23, v16
	s_branch .LBB0_265

; DEVI void phase11(const Params& P, int l, int pass, char* smem) {
;     ...
;     for (int p0 = 0; p0 < 32; p0 += 8) {
;       uint4 ru[8], rv[8];
; #pragma unroll
;       for (int i = 0; i < 8; ++i) {
;         int e = tope[w * 32 + p0 + i];
;         ru[i] = *reinterpret_cast<const uint4*>(UT + (long)e * 1024 + lane * 16);
;         rv[i] = *reinterpret_cast<const uint4*>(VTb + (long)e * 1024 + lane * 16);
;       }
;       float dsum[8];
; #pragma unroll
;       for (int i = 0; i < 8; ++i) {
;         f32x2 f[8];
;         dec16(ru[i], f);
;         f32x2 acc = f[0] * xv[0];
; #pragma unroll
;         for (int q = 1; q < 8; ++q) acc = __builtin_elementwise_fma(f[q], xv[q], acc);
;         dsum[i] = acc.x + acc.y;
.LBB0_265:
	ds_read_b128 v[242:245], v153 offset:512
	ds_read_b128 v[246:249], v153 offset:528
	s_waitcnt lgkmcnt(1)
	v_lshl_add_u32 v234, v242, 10, v250
	v_lshl_add_u32 v235, v243, 10, v250
	v_lshl_add_u32 v236, v244, 10, v250
	v_lshl_add_u32 v237, v245, 10, v250
	global_load_dwordx4 v[154:157], v234, s[60:61]
	global_load_dwordx4 v[60:63], v234, s[62:63]
	global_load_dwordx4 v[158:161], v235, s[60:61]
	global_load_dwordx4 v[56:59], v235, s[62:63]
	global_load_dwordx4 v[162:165], v236, s[60:61]
	global_load_dwordx4 v[52:55], v236, s[62:63]
	global_load_dwordx4 v[166:169], v237, s[60:61]
	global_load_dwordx4 v[48:51], v237, s[62:63]
	s_waitcnt lgkmcnt(0)
	v_lshl_add_u32 v238, v246, 10, v250
	v_lshl_add_u32 v239, v247, 10, v250
	v_lshl_add_u32 v240, v248, 10, v250
	v_lshl_add_u32 v241, v249, 10, v250
	global_load_dwordx4 v[170:173], v238, s[60:61]
	global_load_dwordx4 v[44:47], v238, s[62:63]
	global_load_dwordx4 v[174:177], v239, s[60:61]
	global_load_dwordx4 v[40:43], v239, s[62:63]
	global_load_dwordx4 v[178:181], v240, s[60:61]
	global_load_dwordx4 v[36:39], v240, s[62:63]
	global_load_dwordx4 v[196:199], v241, s[60:61]
	global_load_dwordx4 v[32:35], v241, s[62:63]
	s_waitcnt vmcnt(15)
	v_cvt_pk_f32_fp8_e32 v[182:183], v154
	v_cvt_pk_f32_fp8_sdwa v[200:201], v154 src0_sel:WORD_1
	v_cvt_pk_f32_fp8_e32 v[202:203], v155
	v_cvt_pk_f32_fp8_sdwa v[154:155], v155 src0_sel:WORD_1
	v_cvt_pk_f32_fp8_e32 v[204:205], v156
	v_pk_mul_f32 v[182:183], v[12:13], v[182:183]
	v_cvt_pk_f32_fp8_sdwa v[206:207], v156 src0_sel:WORD_1
	v_pk_fma_f32 v[182:183], v[200:201], v[14:15], v[182:183]
	v_cvt_pk_f32_fp8_e32 v[208:209], v157
	v_pk_fma_f32 v[182:183], v[202:203], v[8:9], v[182:183]
	v_cvt_pk_f32_fp8_sdwa v[156:157], v157 src0_sel:WORD_1
	v_pk_fma_f32 v[154:155], v[154:155], v[10:11], v[182:183]
	s_waitcnt vmcnt(13)
	v_cvt_pk_f32_fp8_e32 v[182:183], v159
	v_pk_fma_f32 v[154:155], v[204:205], v[4:5], v[154:155]
	v_cvt_pk_f32_fp8_e32 v[200:201], v160
	v_pk_fma_f32 v[154:155], v[206:207], v[6:7], v[154:155]
	v_cvt_pk_f32_fp8_sdwa v[202:203], v160 src0_sel:WORD_1
	v_pk_fma_f32 v[154:155], v[208:209], v[0:1], v[154:155]
	v_cvt_pk_f32_fp8_e32 v[204:205], v161
	v_pk_fma_f32 v[154:155], v[156:157], v[2:3], v[154:155]
	v_cvt_pk_f32_fp8_sdwa v[156:157], v158 src0_sel:WORD_1
	v_add_f32_e32 v206, v154, v155
	v_cvt_pk_f32_fp8_e32 v[154:155], v158
	v_cvt_pk_f32_fp8_sdwa v[158:159], v159 src0_sel:WORD_1
	v_cvt_pk_f32_fp8_sdwa v[160:161], v161 src0_sel:WORD_1
	v_pk_mul_f32 v[154:155], v[12:13], v[154:155]
	s_nop 0
	v_pk_fma_f32 v[154:155], v[156:157], v[14:15], v[154:155]
	s_waitcnt vmcnt(11)
	v_cvt_pk_f32_fp8_sdwa v[156:157], v162 src0_sel:WORD_1
	v_pk_fma_f32 v[154:155], v[182:183], v[8:9], v[154:155]
	v_cvt_pk_f32_fp8_sdwa v[182:183], v164 src0_sel:WORD_1
	v_pk_fma_f32 v[154:155], v[158:159], v[10:11], v[154:155]
	v_cvt_pk_f32_fp8_e32 v[158:159], v163
	v_pk_fma_f32 v[154:155], v[200:201], v[4:5], v[154:155]
	v_cvt_pk_f32_fp8_e32 v[200:201], v165
	v_pk_fma_f32 v[154:155], v[202:203], v[6:7], v[154:155]
	s_nop 0
	v_pk_fma_f32 v[154:155], v[204:205], v[0:1], v[154:155]
	s_nop 0
	v_pk_fma_f32 v[154:155], v[160:161], v[2:3], v[154:155]
	v_cvt_pk_f32_fp8_sdwa v[160:161], v163 src0_sel:WORD_1
	v_add_f32_e32 v202, v154, v155
	v_cvt_pk_f32_fp8_e32 v[154:155], v162
	v_cvt_pk_f32_fp8_e32 v[162:163], v164
	v_cvt_pk_f32_fp8_sdwa v[164:165], v165 src0_sel:WORD_1
	v_pk_mul_f32 v[154:155], v[12:13], v[154:155]
	s_nop 0
	v_pk_fma_f32 v[154:155], v[156:157], v[14:15], v[154:155]
	s_waitcnt vmcnt(9)
	v_cvt_pk_f32_fp8_sdwa v[156:157], v166 src0_sel:WORD_1
	v_pk_fma_f32 v[154:155], v[158:159], v[8:9], v[154:155]
	v_cvt_pk_f32_fp8_e32 v[158:159], v167
	v_pk_fma_f32 v[154:155], v[160:161], v[10:11], v[154:155]
	v_cvt_pk_f32_fp8_sdwa v[160:161], v167 src0_sel:WORD_1
	v_pk_fma_f32 v[154:155], v[162:163], v[4:5], v[154:155]
	v_cvt_pk_f32_fp8_e32 v[162:163], v168
	v_pk_fma_f32 v[154:155], v[182:183], v[6:7], v[154:155]
	s_nop 0
	v_pk_fma_f32 v[154:155], v[200:201], v[0:1], v[154:155]
	s_nop 0
	v_pk_fma_f32 v[154:155], v[164:165], v[2:3], v[154:155]
	v_cvt_pk_f32_fp8_sdwa v[164:165], v168 src0_sel:WORD_1
	v_add_f32_e32 v182, v154, v155
	v_cvt_pk_f32_fp8_e32 v[154:155], v166
	v_cvt_pk_f32_fp8_e32 v[166:167], v169
	v_cvt_pk_f32_fp8_sdwa v[168:169], v169 src0_sel:WORD_1
	v_pk_mul_f32 v[154:155], v[12:13], v[154:155]
	s_nop 0
	v_pk_fma_f32 v[154:155], v[156:157], v[14:15], v[154:155]
	s_waitcnt vmcnt(7)
	v_cvt_pk_f32_fp8_sdwa v[156:157], v170 src0_sel:WORD_1
	v_pk_fma_f32 v[154:155], v[158:159], v[8:9], v[154:155]
	v_cvt_pk_f32_fp8_e32 v[158:159], v171
	v_pk_fma_f32 v[154:155], v[160:161], v[10:11], v[154:155]
	v_cvt_pk_f32_fp8_sdwa v[160:161], v171 src0_sel:WORD_1
	v_pk_fma_f32 v[154:155], v[162:163], v[4:5], v[154:155]
	v_cvt_pk_f32_fp8_e32 v[162:163], v172
	v_pk_fma_f32 v[154:155], v[164:165], v[6:7], v[154:155]
	v_cvt_pk_f32_fp8_sdwa v[164:165], v172 src0_sel:WORD_1
	v_pk_fma_f32 v[154:155], v[166:167], v[0:1], v[154:155]
	v_cvt_pk_f32_fp8_e32 v[166:167], v173
	v_pk_fma_f32 v[154:155], v[168:169], v[2:3], v[154:155]
	v_cvt_pk_f32_fp8_sdwa v[168:169], v173 src0_sel:WORD_1
	v_add_f32_e32 v183, v154, v155
	v_cvt_pk_f32_fp8_e32 v[154:155], v170
	v_pk_mul_f32 v[154:155], v[12:13], v[154:155]
	s_nop 0
	v_pk_fma_f32 v[154:155], v[156:157], v[14:15], v[154:155]
	s_waitcnt vmcnt(5)
; DEVI float geluf_(float x) { return 0.5f * x * (1.f + erff(x * 0.70710678118f)); }
; DEVI void phase11(const Params& P, int l, int pass, char* smem) {
;     ...
;       for (int i = 0; i < 8; ++i) {
;         f32x2 f[8];
;         dec16(ru[i], f);
;         f32x2 acc = f[0] * xv[0];
; #pragma unroll
;         for (int q = 1; q < 8; ++q) acc = __builtin_elementwise_fma(f[q], xv[q], acc);
;         dsum[i] = acc.x + acc.y;
;       }
;       float e4[4], e2[2], e1;
;       {
;         const bool hi = (lane & 32) != 0;
; #pragma unroll
;         for (int i = 0; i < 4; ++i) {
;           float snd = hi ? dsum[i] : dsum[i + 4];
;           float kp = hi ? dsum[i + 4] : dsum[i];
;           e4[i] = kp + __shfl_xor(snd, 32);
;         }
;         const bool hi2 = (lane & 16) != 0;
; #pragma unroll
;         for (int i = 0; i < 2; ++i) {
;           float snd = hi2 ? e4[i] : e4[i + 2];
;           float kp = hi2 ? e4[i + 2] : e4[i];
;           e2[i] = kp + __shfl_xor(snd, 16);
;         }
;         const bool hi3 = (lane & 8) != 0;
;         {
;           float snd = hi3 ? e2[0] : e2[1];
;           float kp = hi3 ? e2[1] : e2[0];
;           e1 = kp + __shfl_xor(snd, 8);
;         }
;         e1 += __shfl_xor(e1, 4); e1 += __shfl_xor(e1, 2); e1 += __shfl_xor(e1, 1);
;       }
;       {
;         int r = ((lane >> 5) & 1) * 4 + ((lane >> 4) & 1) * 2 + ((lane >> 3) & 1);
;         float wv_ = tops[w * 32 + p0 + r] * geluf_(e1 * (1.f / U_SCALE)) * (1.f / V_SCALE);
	v_cvt_pk_f32_fp8_sdwa v[156:157], v174 src0_sel:WORD_1
	v_pk_fma_f32 v[154:155], v[158:159], v[8:9], v[154:155]
	v_cvt_pk_f32_fp8_e32 v[158:159], v175
	v_pk_fma_f32 v[154:155], v[160:161], v[10:11], v[154:155]
	v_cvt_pk_f32_fp8_sdwa v[160:161], v175 src0_sel:WORD_1
	v_pk_fma_f32 v[154:155], v[162:163], v[4:5], v[154:155]
	v_cvt_pk_f32_fp8_e32 v[162:163], v176
	v_pk_fma_f32 v[154:155], v[164:165], v[6:7], v[154:155]
	v_cvt_pk_f32_fp8_sdwa v[164:165], v176 src0_sel:WORD_1
	v_pk_fma_f32 v[154:155], v[166:167], v[0:1], v[154:155]
	v_cvt_pk_f32_fp8_e32 v[166:167], v177
	v_pk_fma_f32 v[154:155], v[168:169], v[2:3], v[154:155]
	v_cvt_pk_f32_fp8_sdwa v[168:169], v177 src0_sel:WORD_1
	v_add_f32_e32 v170, v154, v155
	v_cvt_pk_f32_fp8_e32 v[154:155], v174
	v_pk_mul_f32 v[154:155], v[12:13], v[154:155]
	s_nop 0
	v_pk_fma_f32 v[154:155], v[156:157], v[14:15], v[154:155]
	s_waitcnt vmcnt(3)
	v_cvt_pk_f32_fp8_sdwa v[156:157], v178 src0_sel:WORD_1
	v_pk_fma_f32 v[154:155], v[158:159], v[8:9], v[154:155]
	v_cvt_pk_f32_fp8_e32 v[158:159], v179
	v_pk_fma_f32 v[154:155], v[160:161], v[10:11], v[154:155]
	v_cvt_pk_f32_fp8_sdwa v[160:161], v179 src0_sel:WORD_1
	v_pk_fma_f32 v[154:155], v[162:163], v[4:5], v[154:155]
	v_cvt_pk_f32_fp8_e32 v[162:163], v180
	v_pk_fma_f32 v[154:155], v[164:165], v[6:7], v[154:155]
	v_cvt_pk_f32_fp8_sdwa v[164:165], v180 src0_sel:WORD_1
	v_pk_fma_f32 v[154:155], v[166:167], v[0:1], v[154:155]
	v_cvt_pk_f32_fp8_e32 v[166:167], v181
	v_pk_fma_f32 v[154:155], v[168:169], v[2:3], v[154:155]
	v_cvt_pk_f32_fp8_sdwa v[168:169], v181 src0_sel:WORD_1
	v_add_f32_e32 v171, v154, v155
	v_cvt_pk_f32_fp8_e32 v[154:155], v178
	v_pk_mul_f32 v[154:155], v[12:13], v[154:155]
	s_nop 0
	v_pk_fma_f32 v[154:155], v[156:157], v[14:15], v[154:155]
	s_waitcnt vmcnt(1)
	v_cvt_pk_f32_fp8_sdwa v[156:157], v196 src0_sel:WORD_1
	v_pk_fma_f32 v[154:155], v[158:159], v[8:9], v[154:155]
	v_cvt_pk_f32_fp8_e32 v[158:159], v197
	v_pk_fma_f32 v[154:155], v[160:161], v[10:11], v[154:155]
	v_cvt_pk_f32_fp8_sdwa v[160:161], v197 src0_sel:WORD_1
	v_pk_fma_f32 v[154:155], v[162:163], v[4:5], v[154:155]
	v_cvt_pk_f32_fp8_e32 v[162:163], v198
	v_pk_fma_f32 v[154:155], v[164:165], v[6:7], v[154:155]
	v_cvt_pk_f32_fp8_sdwa v[164:165], v198 src0_sel:WORD_1
	v_pk_fma_f32 v[154:155], v[166:167], v[0:1], v[154:155]
	v_cvt_pk_f32_fp8_e32 v[166:167], v199
	v_pk_fma_f32 v[154:155], v[168:169], v[2:3], v[154:155]
	v_cvt_pk_f32_fp8_sdwa v[168:169], v199 src0_sel:WORD_1
	v_add_f32_e32 v172, v154, v155
	v_cvt_pk_f32_fp8_e32 v[154:155], v196
	v_pk_mul_f32 v[154:155], v[12:13], v[154:155]
	s_nop 0
	v_pk_fma_f32 v[154:155], v[156:157], v[14:15], v[154:155]
	s_nop 0
	v_pk_fma_f32 v[154:155], v[158:159], v[8:9], v[154:155]
	s_nop 0
	v_pk_fma_f32 v[154:155], v[160:161], v[10:11], v[154:155]
	s_nop 0
	v_pk_fma_f32 v[154:155], v[162:163], v[4:5], v[154:155]
	s_nop 0
	v_pk_fma_f32 v[154:155], v[164:165], v[6:7], v[154:155]
	s_nop 0
	v_pk_fma_f32 v[154:155], v[166:167], v[0:1], v[154:155]
	s_nop 0
	v_pk_fma_f32 v[154:155], v[168:169], v[2:3], v[154:155]
	s_nop 0
	v_add_f32_e32 v154, v154, v155
	s_nop 1
	v_permlane32_swap_b32_e32 v206, v170
	v_permlane32_swap_b32_e32 v202, v171
	v_permlane32_swap_b32_e32 v182, v172
	v_permlane32_swap_b32_e32 v183, v154
	s_nop 1
	v_add_f32_e32 v206, v206, v170
	v_add_f32_e32 v202, v202, v171
	v_add_f32_e32 v182, v182, v172
	v_add_f32_e32 v183, v183, v154
	s_nop 1
	v_permlane16_swap_b32_e32 v206, v182
	v_permlane16_swap_b32_e32 v202, v183
	s_nop 1
	v_add_f32_e32 v206, v206, v182
	v_add_f32_e32 v202, v202, v183
	s_nop 1
	v_add_f32_dpp v154, v206, v206 row_ror:8 row_mask:0xf bank_mask:0x3
	v_add_f32_dpp v154, v202, v202 row_ror:8 row_mask:0xf bank_mask:0xc
	s_nop 1
	v_add_f32_dpp v155, v154, v154 row_shl:4 row_mask:0xf bank_mask:0x5
	v_add_f32_dpp v155, v154, v154 row_shr:4 row_mask:0xf bank_mask:0xa
	s_nop 1
	v_add_f32_dpp v156, v155, v155 quad_perm:[2,3,0,1] row_mask:0xf bank_mask:0xf
	s_nop 1
	v_add_f32_dpp v154, v156, v156 quad_perm:[1,0,3,2] row_mask:0xf bank_mask:0xf
	v_add_u32_e32 v155, v153, v148
	ds_read_b32 v156, v155
	v_mul_f32_e32 v154, 0x3c800000, v154
	v_mul_f32_e32 v157, 0x3f3504f3, v154
	v_cmp_nlt_f32_e64 s[56:57], |v157|, 1.0
	s_and_saveexec_b64 s[58:59], s[56:57]
	s_xor_b64 s[56:57], exec, s[58:59]
	s_cbranch_execz .LBB0_268
	v_fma_f32 v158, |v157|, s70, v188
	v_fma_f32 v158, |v157|, v158, s71
	v_fma_f32 v158, |v157|, v158, s3
	v_fma_f32 v158, |v157|, v158, s96
	v_fma_f32 v158, |v157|, v158, s97
	v_fma_f32 v158, |v157|, v158, s87
	v_fma_f32 v158, |v157|, v158, |v157|
	v_mul_f32_e32 v159, 0xbfb8aa3b, v158
	v_fma_f32 v160, v158, s94, -v159
	v_rndne_f32_e32 v161, v159
	v_fmac_f32_e32 v160, 0xb2a5705f, v158
	v_sub_f32_e32 v159, v159, v161
	v_add_f32_e32 v159, v159, v160
	v_cvt_i32_f32_e32 v160, v161
	v_exp_f32_e32 v159, v159
	v_cmp_nlt_f32_e32 vcc, s95, v158
	v_ldexp_f32 v159, v159, v160
	s_nop 0
	v_cndmask_b32_e32 v159, 0, v159, vcc
	v_cmp_ngt_f32_e32 vcc, s68, v158
	s_nop 1
	v_cndmask_b32_e32 v158, v189, v159, vcc
	v_sub_f32_e32 v158, 1.0, v158
	s_andn2_saveexec_b64 s[56:57], s[56:57]
	s_cbranch_execnz .LBB0_269

; DEVI void phase11(const Params& P, int l, int pass, char* smem) {
;     ...
;     float s = wave_sum(y[0] + y[1] + y[2] + y[3]);
;     if (lane == 0) stat[w] = s;
;     __syncthreads();
;     float mu = (stat[0] + stat[1] + stat[2] + stat[3]) * (1.f / 1024.f);
;     float ss = 0.f;
; #pragma unroll
;     for (int i = 0; i < 4; ++i) { float dl = y[i] - mu; ss += dl * dl; }
;     ss = wave_sum(ss);
;     if (lane == 0) stat[4 + w] = ss;
;     __syncthreads();
;     float rs = rsqrtf((stat[4] + stat[5] + stat[6] + stat[7]) * (1.f / 1024.f) + 1e-5f);
.LBB0_271:
	v_lshl_add_u64 v[0:1], v[104:105], 2, s[54:55]
	ds_write_b128 v131, v[16:19] offset:13824
	ds_write_b128 v131, v[28:31] offset:13840
	ds_write_b128 v131, v[24:27] offset:13856
	ds_write_b128 v131, v[20:23] offset:13872
	s_waitcnt lgkmcnt(0)
	s_barrier
	s_add_i32 s56, s74, s23
	s_cmp_lt_i32 s56, s1
	s_cselect_b32 s56, s56, s74
	s_ashr_i32 s57, s56, 31
	s_lshl_b64 s[56:57], s[56:57], 13
	v_lshl_add_u64 v[218:219], v[102:103], 0, s[56:57]
	global_load_dwordx2 v[210:211], v[218:219], off sc1
	global_load_dwordx2 v[212:213], v[218:219], off offset:2048 sc1
	v_add_co_u32_e32 v218, vcc, 0x1000, v218
	s_nop 1
	v_addc_co_u32_e32 v219, vcc, 0, v219, vcc
	global_load_dwordx2 v[214:215], v[218:219], off sc1
	global_load_dwordx2 v[216:217], v[218:219], off offset:2048 sc1
	ds_read_b128 v[8:11], v151 offset:13824
	ds_read_b128 v[12:15], v151 offset:17920
	ds_read_b128 v[16:19], v151 offset:22016
	ds_read_b128 v[20:23], v151 offset:26112
	s_waitcnt lgkmcnt(2)
	v_pk_add_f32 v[2:3], v[8:9], v[12:13]
	v_pk_add_f32 v[8:9], v[10:11], v[14:15]
	s_waitcnt lgkmcnt(1)
	v_pk_add_f32 v[2:3], v[2:3], v[16:17]
	v_pk_add_f32 v[8:9], v[8:9], v[18:19]
	s_waitcnt lgkmcnt(0)
	v_pk_add_f32 v[2:3], v[2:3], v[20:21]
	v_pk_add_f32 v[8:9], v[8:9], v[22:23]
	v_pk_fma_f32 v[4:5], v[228:229], s[92:93], v[2:3] op_sel_hi:[1,0,1]
	v_pk_fma_f32 v[2:3], v[230:231], s[92:93], v[8:9] op_sel_hi:[1,0,1]
	v_add_f32_e32 v6, v4, v5
	v_add_f32_e32 v6, v6, v2
	v_add_f32_e32 v6, v6, v3
	v_mov_b32_e32 v7, v6
	s_nop 1
	v_permlane32_swap_b32_e32 v7, v6
	s_nop 1
	v_add_f32_e32 v6, v6, v7
	v_mov_b32_e32 v7, v6
	s_nop 1
	v_permlane16_swap_b32_e32 v7, v6
	s_nop 1
	v_add_f32_e32 v6, v6, v7
	s_nop 1
	v_add_f32_dpp v7, v6, v6 row_ror:8 row_mask:0xf bank_mask:0xf
	s_nop 1
	v_add_f32_dpp v6, v7, v7 row_shl:4 row_mask:0xf bank_mask:0x5
	v_add_f32_dpp v6, v7, v7 row_shr:4 row_mask:0xf bank_mask:0xa
	s_nop 1
	v_add_f32_dpp v7, v6, v6 quad_perm:[2,3,0,1] row_mask:0xf bank_mask:0xf
	s_nop 1
	v_add_f32_dpp v6, v7, v7 quad_perm:[1,0,3,2] row_mask:0xf bank_mask:0xf
	s_and_saveexec_b64 s[54:55], s[52:53]
	s_cbranch_execz .LBB0_273
	ds_write_b32 v152, v6 offset:30208
.LBB0_273:
	s_or_b64 exec, exec, s[54:55]
	s_waitcnt lgkmcnt(0)
	s_barrier
	ds_read_b128 v[6:9], v89 offset:30208
	s_waitcnt lgkmcnt(0)
	v_add_f32_e32 v6, v6, v7
	v_add_f32_e32 v6, v6, v8
	v_add_f32_e32 v6, v6, v9
	v_mul_f32_e32 v6, 0x3a800000, v6
	v_pk_add_f32 v[4:5], v[4:5], v[6:7] op_sel_hi:[1,0] neg_lo:[0,1] neg_hi:[0,1]
	v_pk_add_f32 v[2:3], v[2:3], v[6:7] op_sel_hi:[1,0] neg_lo:[0,1] neg_hi:[0,1]
	v_pk_mul_f32 v[6:7], v[4:5], v[4:5]
	v_pk_mul_f32 v[8:9], v[2:3], v[2:3]
	v_add_f32_e32 v6, v6, v7
	v_add_f32_e32 v6, v8, v6
	v_add_f32_e32 v6, v9, v6
	v_mov_b32_e32 v7, v6
	s_nop 1
	v_permlane32_swap_b32_e32 v7, v6
	s_nop 1
	v_add_f32_e32 v6, v6, v7
	v_mov_b32_e32 v7, v6
	s_nop 1
	v_permlane16_swap_b32_e32 v7, v6
	s_nop 1
	v_add_f32_e32 v6, v6, v7
	s_nop 1
	v_add_f32_dpp v7, v6, v6 row_ror:8 row_mask:0xf bank_mask:0xf
	s_nop 1
	v_add_f32_dpp v6, v7, v7 row_shl:4 row_mask:0xf bank_mask:0x5
	v_add_f32_dpp v6, v7, v7 row_shr:4 row_mask:0xf bank_mask:0xa
	s_nop 1
	v_add_f32_dpp v7, v6, v6 quad_perm:[2,3,0,1] row_mask:0xf bank_mask:0xf
	s_nop 1
	v_add_f32_dpp v6, v7, v7 quad_perm:[1,0,3,2] row_mask:0xf bank_mask:0xf
	s_and_saveexec_b64 s[54:55], s[52:53]
	s_cbranch_execz .LBB0_128
	ds_write_b32 v152, v6 offset:30224
	s_branch .LBB0_128

; template <int GATE>
; DEVI void gemm_core_t(f32x4 (&acc)[4][4], const bfu* __restrict__ A, int lda,
;                     const bfu* __restrict__ B, int ldb, int K, char* smem, int tid, const bfu* __restrict__ B2 = nullptr) {
;     ...
;   for (int t = 0; t < nt; ++t) {
;     asm volatile("s_waitcnt vmcnt(0)" ::: "memory");
;     __syncthreads();
;     char* cur = smem + (t & 1) * 32768;
;     if (t + 1 < nt) {
;       char* nx = smem + ((t + 1) & 1) * 32768;
;       stage_tile(A, lda, (t + 1) * 64, nx, tid);
;       if (GATE) stage_tile_gate(B, B2, (t + 1) * 64, nx + 16384, tid); else stage_tile(B, ldb, (t + 1) * 64, nx + 16384, tid);
;     }
; #pragma unroll
;     for (int kk = 0; kk < 2; ++kk) {
;       bf16x8 af[4], bfr[4];
; #pragma unroll
;       for (int m = 0; m < 4; ++m) af[m] = ldfrag(cur, wr * 64 + m * 16 + fr, kk * 4 + fq);
; #pragma unroll
;       for (int n = 0; n < 4; ++n) bfr[n] = ldfrag(cur + 16384, wc * 64 + n * 16 + fr, kk * 4 + fq);
; #pragma unroll
;       for (int m = 0; m < 4; ++m)
; #pragma unroll
;         for (int n = 0; n < 4; ++n)
;           acc[m][n] = __builtin_amdgcn_mfma_f32_16x16x32_bf16(af[m], bfr[n], acc[m][n], 0, 0, 0);
;     }
.LBB0_287:
	s_add_i32 s41, s1, 0xffff8000
	s_and_b32 s44, s41, 0x8000
	s_and_b32 s41, s1, 0x8000
	v_add_u32_e32 v143, s41, v91
	v_or_b32_e32 v147, s44, v174
	v_readfirstlane_b32 s45, v143
	v_add_u32_e32 v143, v147, v175
	v_add_u32_e32 v147, v147, v176
	s_waitcnt vmcnt(0)
	s_waitcnt vmcnt(0) lgkmcnt(0)
	s_barrier
	ds_read_b128 v[202:205], v143
	ds_read_b128 v[218:221], v147 offset:16384
	ds_read_b128 v[222:225], v147 offset:18432
	ds_read_b128 v[226:229], v147 offset:20480
	ds_read_b128 v[230:233], v147 offset:22528
	ds_read_b128 v[206:209], v143 offset:2048
	ds_read_b128 v[210:213], v143 offset:4096
	ds_read_b128 v[214:217], v143 offset:6144
	v_lshl_add_u64 v[250:251], v[156:157], 0, s[42:43]
	s_mov_b32 m0, s45
	s_add_i32 s45, s45, 0x1000
	global_load_lds_dwordx4 v[250:251], off
	v_or_b32_e32 v147, s44, v177
	v_add_u32_e32 v143, v147, v175
	v_add_u32_e32 v147, v147, v176
	ds_read_b128 v[234:237], v147 offset:16384
	ds_read_b128 v[238:241], v147 offset:18432
	ds_read_b128 v[242:245], v147 offset:20480
	ds_read_b128 v[246:249], v147 offset:22528
	v_lshl_add_u64 v[250:251], v[158:159], 0, s[42:43]
	s_mov_b32 m0, s45
	s_add_i32 s45, s45, 0x1000
	global_load_lds_dwordx4 v[250:251], off
	s_waitcnt lgkmcnt(7)
	v_mfma_f32_16x16x32_bf16 v[60:63], v[202:205], v[218:221], v[60:63]
	v_mfma_f32_16x16x32_bf16 v[56:59], v[202:205], v[222:225], v[56:59]
	v_mfma_f32_16x16x32_bf16 v[52:55], v[202:205], v[226:229], v[52:55]
	v_mfma_f32_16x16x32_bf16 v[48:51], v[202:205], v[230:233], v[48:51]
	ds_read_b128 v[202:205], v143
	v_lshl_add_u64 v[250:251], v[160:161], 0, s[42:43]
	s_mov_b32 m0, s45
	s_add_i32 s45, s45, 0x1000
	global_load_lds_dwordx4 v[250:251], off
	s_waitcnt lgkmcnt(7)
	v_mfma_f32_16x16x32_bf16 v[44:47], v[206:209], v[218:221], v[44:47]
	v_mfma_f32_16x16x32_bf16 v[40:43], v[206:209], v[222:225], v[40:43]
	v_mfma_f32_16x16x32_bf16 v[36:39], v[206:209], v[226:229], v[36:39]
	v_mfma_f32_16x16x32_bf16 v[32:35], v[206:209], v[230:233], v[32:35]
	ds_read_b128 v[206:209], v143 offset:2048
	v_lshl_add_u64 v[250:251], v[162:163], 0, s[42:43]
	s_mov_b32 m0, s45
	s_add_i32 s45, s45, 0x1000
	global_load_lds_dwordx4 v[250:251], off
	s_waitcnt lgkmcnt(7)
	v_mfma_f32_16x16x32_bf16 v[28:31], v[210:213], v[218:221], v[28:31]
	v_mfma_f32_16x16x32_bf16 v[24:27], v[210:213], v[222:225], v[24:27]
	v_mfma_f32_16x16x32_bf16 v[20:23], v[210:213], v[226:229], v[20:23]
	v_mfma_f32_16x16x32_bf16 v[16:19], v[210:213], v[230:233], v[16:19]
	ds_read_b128 v[210:213], v143 offset:4096
	v_lshl_add_u64 v[250:251], v[164:165], 0, s[42:43]
	s_mov_b32 m0, s45
	s_add_i32 s45, s45, 0x1000
	global_load_lds_dwordx4 v[250:251], off
	s_waitcnt lgkmcnt(7)
	v_mfma_f32_16x16x32_bf16 v[12:15], v[214:217], v[218:221], v[12:15]
	v_mfma_f32_16x16x32_bf16 v[8:11], v[214:217], v[222:225], v[8:11]
	v_mfma_f32_16x16x32_bf16 v[4:7], v[214:217], v[226:229], v[4:7]
	v_mfma_f32_16x16x32_bf16 v[0:3], v[214:217], v[230:233], v[0:3]
	ds_read_b128 v[214:217], v143 offset:6144
	v_lshl_add_u64 v[250:251], v[166:167], 0, s[42:43]
	s_mov_b32 m0, s45
	s_add_i32 s45, s45, 0x1000
	global_load_lds_dwordx4 v[250:251], off
	s_waitcnt lgkmcnt(3)
	v_mfma_f32_16x16x32_bf16 v[60:63], v[202:205], v[234:237], v[60:63]
	v_mfma_f32_16x16x32_bf16 v[56:59], v[202:205], v[238:241], v[56:59]
	v_mfma_f32_16x16x32_bf16 v[52:55], v[202:205], v[242:245], v[52:55]
	v_mfma_f32_16x16x32_bf16 v[48:51], v[202:205], v[246:249], v[48:51]
	v_lshl_add_u64 v[250:251], v[168:169], 0, s[42:43]
	s_mov_b32 m0, s45
	s_add_i32 s45, s45, 0x1000
	global_load_lds_dwordx4 v[250:251], off
	s_waitcnt lgkmcnt(2)
	v_mfma_f32_16x16x32_bf16 v[44:47], v[206:209], v[234:237], v[44:47]
	v_mfma_f32_16x16x32_bf16 v[40:43], v[206:209], v[238:241], v[40:43]
	v_mfma_f32_16x16x32_bf16 v[36:39], v[206:209], v[242:245], v[36:39]
	v_mfma_f32_16x16x32_bf16 v[32:35], v[206:209], v[246:249], v[32:35]
	v_lshl_add_u64 v[250:251], v[170:171], 0, s[42:43]
	s_mov_b32 m0, s45
	s_add_i32 s45, s45, 0x1000
	global_load_lds_dwordx4 v[250:251], off
	s_waitcnt lgkmcnt(1)
	v_mfma_f32_16x16x32_bf16 v[28:31], v[210:213], v[234:237], v[28:31]
	v_mfma_f32_16x16x32_bf16 v[24:27], v[210:213], v[238:241], v[24:27]
	v_mfma_f32_16x16x32_bf16 v[20:23], v[210:213], v[242:245], v[20:23]
	v_mfma_f32_16x16x32_bf16 v[16:19], v[210:213], v[246:249], v[16:19]
	s_waitcnt lgkmcnt(0)
	v_mfma_f32_16x16x32_bf16 v[12:15], v[214:217], v[234:237], v[12:15]
	v_mfma_f32_16x16x32_bf16 v[8:11], v[214:217], v[238:241], v[8:11]
	v_mfma_f32_16x16x32_bf16 v[4:7], v[214:217], v[242:245], v[4:7]
	v_mfma_f32_16x16x32_bf16 v[0:3], v[214:217], v[246:249], v[0:3]
	s_add_u32 s42, s42, 0x80
	s_addc_u32 s43, s43, 0
	s_add_i32 s1, s1, 0x8000
	s_cmpk_lg_i32 s42, 0x780
	s_cbranch_scc1 .LBB0_287
; template <int GATE>
; DEVI void gemm_core_t(f32x4 (&acc)[4][4], const bfu* __restrict__ A, int lda,
;                     const bfu* __restrict__ B, int ldb, int K, char* smem, int tid, const bfu* __restrict__ B2 = nullptr) {
;     ...
;   for (int t = 0; t < nt; ++t) {
;     asm volatile("s_waitcnt vmcnt(0)" ::: "memory");
;     __syncthreads();
;     char* cur = smem + (t & 1) * 32768;
;     if (t + 1 < nt) {
;       char* nx = smem + ((t + 1) & 1) * 32768;
;       stage_tile(A, lda, (t + 1) * 64, nx, tid);
;       if (GATE) stage_tile_gate(B, B2, (t + 1) * 64, nx + 16384, tid); else stage_tile(B, ldb, (t + 1) * 64, nx + 16384, tid);
;     }
; #pragma unroll
;     for (int kk = 0; kk < 2; ++kk) {
;       bf16x8 af[4], bfr[4];
; #pragma unroll
;       for (int m = 0; m < 4; ++m) af[m] = ldfrag(cur, wr * 64 + m * 16 + fr, kk * 4 + fq);
; #pragma unroll
;       for (int n = 0; n < 4; ++n) bfr[n] = ldfrag(cur + 16384, wc * 64 + n * 16 + fr, kk * 4 + fq);
; #pragma unroll
;       for (int m = 0; m < 4; ++m)
; #pragma unroll
;         for (int n = 0; n < 4; ++n)
;           acc[m][n] = __builtin_amdgcn_mfma_f32_16x16x32_bf16(af[m], bfr[n], acc[m][n], 0, 0, 0);
;     }
; DEVI void epi_store_bf16(const f32x4 (&acc)[4][4], const float* colbias, bfu* dst, long ld, char* smem, int tid) {
;     ...
;   for (int n = 0; n < 4; ++n) {
;     const int col = wc * 64 + n * 16 + fr;
;     const float bias = colbias ? colbias[col] : 0.f;
	v_add_u32_e32 v143, s41, v174
	v_add_u32_e32 v147, v143, v175
	s_waitcnt vmcnt(0)
	s_waitcnt vmcnt(0)
	s_barrier
	ds_read_b128 v[156:159], v147
	v_add_u32_e32 v143, v143, v176
	ds_read_b128 v[168:171], v143 offset:20480
	ds_read_b128 v[160:163], v143 offset:16384
	ds_read_b128 v[164:167], v143 offset:18432
	s_waitcnt lgkmcnt(2)
	v_mfma_f32_16x16x32_bf16 v[202:205], v[156:159], v[168:171], v[52:55]
	s_nop 2
	ds_read_b128 v[52:55], v143 offset:22528
	s_lshl_b32 s42, s40, 7
	s_ashr_i32 s43, s42, 31
	s_waitcnt lgkmcnt(2)
	v_mfma_f32_16x16x32_bf16 v[60:63], v[156:159], v[160:163], v[60:63]
	v_readlane_b32 s4, v254, 60
	v_readlane_b32 s5, v254, 61
	v_mov_b32_e32 v151, 0
	s_waitcnt lgkmcnt(1)
	v_mfma_f32_16x16x32_bf16 v[56:59], v[156:159], v[164:167], v[56:59]
	s_waitcnt lgkmcnt(0)
	v_mfma_f32_16x16x32_bf16 v[48:51], v[156:159], v[52:55], v[48:51]
	ds_read_b128 v[156:159], v147 offset:2048
	s_waitcnt lgkmcnt(0)
	v_mfma_f32_16x16x32_bf16 v[206:209], v[156:159], v[168:171], v[36:39]
	s_nop 2
	ds_read_b128 v[36:39], v147 offset:4096
	s_waitcnt lgkmcnt(0)
	v_mfma_f32_16x16x32_bf16 v[214:217], v[36:39], v[52:55], v[16:19]
	s_nop 2
	ds_read_b128 v[16:19], v147 offset:6144
	v_mov_b32_e32 v147, 0
	v_mfma_f32_16x16x32_bf16 v[44:47], v[156:159], v[160:163], v[44:47]
	v_mfma_f32_16x16x32_bf16 v[28:31], v[36:39], v[160:163], v[28:31]
	s_waitcnt lgkmcnt(0)
	v_mfma_f32_16x16x32_bf16 v[12:15], v[16:19], v[160:163], v[12:15]
	v_mfma_f32_16x16x32_bf16 v[160:163], v[16:19], v[164:167], v[8:11]
	s_nop 2
	v_add_u32_e32 v8, s41, v177
	v_add_u32_e32 v143, v8, v175
	v_mfma_f32_16x16x32_bf16 v[40:43], v[156:159], v[164:167], v[40:43]
	s_lshl_b64 s[40:41], s[42:43], 2
	s_add_u32 s44, s47, s40
	s_addc_u32 s45, s48, s41
	v_lshlrev_b32_e32 v236, 2, v106
	global_load_dword v151, v236, s[44:45]
	global_load_dword v147, v236, s[44:45] offset:64
	global_load_dword v234, v236, s[44:45] offset:128
	global_load_dword v235, v236, s[44:45] offset:192
	v_mfma_f32_16x16x32_bf16 v[32:35], v[156:159], v[52:55], v[32:35]
	s_andn2_b64 vcc, exec, s[4:5]
	v_mfma_f32_16x16x32_bf16 v[156:159], v[36:39], v[164:167], v[24:27]
	v_mfma_f32_16x16x32_bf16 v[164:167], v[16:19], v[168:171], v[4:7]
	s_nop 2
	ds_read_b128 v[4:7], v143
	v_mfma_f32_16x16x32_bf16 v[210:213], v[36:39], v[168:171], v[20:23]
	v_mfma_f32_16x16x32_bf16 v[168:171], v[16:19], v[52:55], v[0:3]
	s_nop 2
	v_add_u32_e32 v0, v8, v176
	ds_read_b128 v[226:229], v0 offset:20480
	ds_read_b128 v[218:221], v0 offset:16384
	ds_read_b128 v[222:225], v0 offset:18432
	s_waitcnt lgkmcnt(2)
	v_mfma_f32_16x16x32_bf16 v[20:23], v[4:7], v[226:229], v[202:205]
	ds_read_b128 v[8:11], v143 offset:4096
	s_nop 1
	ds_read_b128 v[202:205], v0 offset:22528
	s_waitcnt lgkmcnt(3)
	v_mfma_f32_16x16x32_bf16 v[52:55], v[4:7], v[218:221], v[60:63]
	s_waitcnt lgkmcnt(2)
	v_mfma_f32_16x16x32_bf16 v[36:39], v[4:7], v[222:225], v[56:59]
	s_waitcnt lgkmcnt(0)
	v_mfma_f32_16x16x32_bf16 v[0:3], v[4:7], v[202:205], v[48:51]
	ds_read_b128 v[4:7], v143 offset:2048
	s_waitcnt lgkmcnt(0)
	v_mfma_f32_16x16x32_bf16 v[60:63], v[4:7], v[218:221], v[44:47]
	v_mfma_f32_16x16x32_bf16 v[40:43], v[4:7], v[222:225], v[40:43]
	v_mfma_f32_16x16x32_bf16 v[24:27], v[4:7], v[226:229], v[206:209]
	v_mfma_f32_16x16x32_bf16 v[4:7], v[4:7], v[202:205], v[32:35]
	v_mfma_f32_16x16x32_bf16 v[32:35], v[8:11], v[222:225], v[156:159]
	s_nop 2
	ds_read_b128 v[156:159], v143 offset:6144
	s_waitcnt lgkmcnt(0)
	v_mfma_f32_16x16x32_bf16 v[56:59], v[156:159], v[218:221], v[12:15]
	s_nop 2
	v_cndmask_b32_e64 v12, 0, 1, s[4:5]
	v_cmp_ne_u32_e64 s[40:41], 1, v12
	v_lshlrev_b32_e32 v143, 2, v106
	v_mfma_f32_16x16x32_bf16 v[48:51], v[8:11], v[218:221], v[28:31]
	s_barrier
	v_mfma_f32_16x16x32_bf16 v[16:19], v[8:11], v[226:229], v[210:213]
	v_mfma_f32_16x16x32_bf16 v[8:11], v[8:11], v[202:205], v[214:217]
	v_mfma_f32_16x16x32_bf16 v[44:47], v[156:159], v[222:225], v[160:163]
	v_mfma_f32_16x16x32_bf16 v[28:31], v[156:159], v[226:229], v[164:167]
	v_mfma_f32_16x16x32_bf16 v[12:15], v[156:159], v[202:205], v[168:171]

; DEVI void epi_store_bf16(const f32x4 (&acc)[4][4], const float* colbias, bfu* dst, long ld, char* smem, int tid) {
;     ...
; #pragma unroll
;   for (int n = 0; n < 4; ++n) {
;     const int col = wc * 64 + n * 16 + fr;
;     const float bias = colbias ? colbias[col] : 0.f;
; #pragma unroll
;     for (int m = 0; m < 4; ++m)
; #pragma unroll
;       for (int j = 0; j < 4; ++j)
;         T[(wr * 64 + m * 16 + fq * 4 + j) * 136 + col] = f2b(acc[m][n][j] + bias);
;   }
;   __syncthreads();
.LBB0_292:
	s_waitcnt vmcnt(0)
	v_add_f32_e32 v36, v36, v147
	v_bfe_u32 v48, v36, 16, 1
	v_add3_u32 v36, v36, v48, s39
	ds_write_b16_d16_hi v178, v36 offset:32
	v_add_f32_e32 v36, v37, v147
	v_bfe_u32 v37, v36, 16, 1
	v_add3_u32 v36, v36, v37, s39
	ds_write_b16_d16_hi v178, v36 offset:304
	v_add_f32_e32 v36, v38, v147
	v_bfe_u32 v37, v36, 16, 1
	v_add3_u32 v36, v36, v37, s39
	ds_write_b16_d16_hi v178, v36 offset:576
	v_add_f32_e32 v36, v39, v147
	v_bfe_u32 v37, v36, 16, 1
	v_add3_u32 v36, v36, v37, s39
	ds_write_b16_d16_hi v178, v36 offset:848
	v_add_f32_e32 v36, v40, v147
	v_bfe_u32 v37, v36, 16, 1
	v_add3_u32 v36, v36, v37, s39
	ds_write_b16_d16_hi v178, v36 offset:4384
	v_add_f32_e32 v36, v41, v147
	v_bfe_u32 v37, v36, 16, 1
	v_add3_u32 v36, v36, v37, s39
	ds_write_b16_d16_hi v178, v36 offset:4656
	v_add_f32_e32 v36, v42, v147
	v_bfe_u32 v37, v36, 16, 1
	v_add3_u32 v36, v36, v37, s39
	ds_write_b16_d16_hi v178, v36 offset:4928
	v_add_f32_e32 v36, v43, v147
	v_bfe_u32 v37, v36, 16, 1
	v_add3_u32 v36, v36, v37, s39
	v_add_f32_e32 v32, v32, v147
	ds_write_b16_d16_hi v178, v36 offset:5200
	v_bfe_u32 v36, v32, 16, 1
	v_add3_u32 v32, v32, v36, s39
	ds_write_b16_d16_hi v178, v32 offset:8736
	v_add_f32_e32 v32, v33, v147
	v_bfe_u32 v33, v32, 16, 1
	v_add3_u32 v32, v32, v33, s39
	ds_write_b16_d16_hi v178, v32 offset:9008
	v_add_f32_e32 v32, v34, v147
	v_bfe_u32 v33, v32, 16, 1
	v_add3_u32 v32, v32, v33, s39
	ds_write_b16_d16_hi v178, v32 offset:9280
	v_add_f32_e32 v32, v35, v147
	v_bfe_u32 v33, v32, 16, 1
	v_add3_u32 v32, v32, v33, s39
	ds_write_b16_d16_hi v178, v32 offset:9552
	v_add_f32_e32 v32, v44, v147
	v_bfe_u32 v33, v32, 16, 1
	v_add3_u32 v32, v32, v33, s39
	ds_write_b16_d16_hi v178, v32 offset:13088
	v_add_f32_e32 v32, v45, v147
	v_bfe_u32 v33, v32, 16, 1
	v_add3_u32 v32, v32, v33, s39
	ds_write_b16_d16_hi v178, v32 offset:13360
	v_add_f32_e32 v32, v46, v147
	v_bfe_u32 v33, v32, 16, 1
	v_add3_u32 v32, v32, v33, s39
	ds_write_b16_d16_hi v178, v32 offset:13632
	v_add_f32_e32 v32, v47, v147
	v_bfe_u32 v33, v32, 16, 1
	v_add3_u32 v32, v32, v33, s39
	ds_write_b16_d16_hi v178, v32 offset:13904
	v_mov_b32_e32 v32, v235
	v_mov_b32_e32 v33, v234
.LBB0_294:
	s_waitcnt vmcnt(0)
	v_add_f32_e32 v20, v20, v33
	v_bfe_u32 v34, v20, 16, 1
	v_add3_u32 v20, v20, v34, s39
	ds_write_b16_d16_hi v178, v20 offset:64
	v_add_f32_e32 v20, v21, v33
	v_bfe_u32 v21, v20, 16, 1
	v_add3_u32 v20, v20, v21, s39
	ds_write_b16_d16_hi v178, v20 offset:336
	v_add_f32_e32 v20, v22, v33
	v_bfe_u32 v21, v20, 16, 1
	v_add3_u32 v20, v20, v21, s39
	ds_write_b16_d16_hi v178, v20 offset:608
	v_add_f32_e32 v20, v23, v33
	v_bfe_u32 v21, v20, 16, 1
	v_add3_u32 v20, v20, v21, s39
	ds_write_b16_d16_hi v178, v20 offset:880
	v_add_f32_e32 v20, v24, v33
	v_bfe_u32 v21, v20, 16, 1
	v_add3_u32 v20, v20, v21, s39
	ds_write_b16_d16_hi v178, v20 offset:4416
	v_add_f32_e32 v20, v25, v33
	v_bfe_u32 v21, v20, 16, 1
	v_add3_u32 v20, v20, v21, s39
	ds_write_b16_d16_hi v178, v20 offset:4688
	v_add_f32_e32 v20, v26, v33
	v_bfe_u32 v21, v20, 16, 1
	v_add3_u32 v20, v20, v21, s39
	ds_write_b16_d16_hi v178, v20 offset:4960
	v_add_f32_e32 v20, v27, v33
	v_bfe_u32 v21, v20, 16, 1
	v_add3_u32 v20, v20, v21, s39
	v_add_f32_e32 v16, v16, v33
	ds_write_b16_d16_hi v178, v20 offset:5232
	v_bfe_u32 v20, v16, 16, 1
	v_add3_u32 v16, v16, v20, s39
	ds_write_b16_d16_hi v178, v16 offset:8768
	v_add_f32_e32 v16, v17, v33
	v_bfe_u32 v17, v16, 16, 1
	v_add3_u32 v16, v16, v17, s39
	ds_write_b16_d16_hi v178, v16 offset:9040
	v_add_f32_e32 v16, v18, v33
	v_bfe_u32 v17, v16, 16, 1
	v_add3_u32 v16, v16, v17, s39
	ds_write_b16_d16_hi v178, v16 offset:9312
	v_add_f32_e32 v16, v19, v33
	v_bfe_u32 v17, v16, 16, 1
	v_add3_u32 v16, v16, v17, s39
	ds_write_b16_d16_hi v178, v16 offset:9584
	v_add_f32_e32 v16, v28, v33
	v_bfe_u32 v17, v16, 16, 1
	v_add3_u32 v16, v16, v17, s39
	ds_write_b16_d16_hi v178, v16 offset:13120
	v_add_f32_e32 v16, v29, v33
	v_bfe_u32 v17, v16, 16, 1
	v_add3_u32 v16, v16, v17, s39
	ds_write_b16_d16_hi v178, v16 offset:13392
	v_add_f32_e32 v16, v30, v33
	v_bfe_u32 v17, v16, 16, 1
	v_add3_u32 v16, v16, v17, s39
	ds_write_b16_d16_hi v178, v16 offset:13664
	v_add_f32_e32 v16, v31, v33
	v_bfe_u32 v17, v16, 16, 1
	v_add3_u32 v16, v16, v17, s39
	s_and_b64 vcc, exec, s[40:41]
	ds_write_b16_d16_hi v178, v16 offset:13936
	s_branch .LBB0_281
